# rg_b carry computed as a parallel composition of per-chunk affine maps across the 8 waves (LDS exchange) instead of a serial 63-step chain per wave
# baseline (speedup 1.0000x reference)
; __device__ __forceinline__ float bf2f(unsigned h) { return __uint_as_float(h << 16); }
; __device__ __forceinline__ void rg_b_unit(const Params& p, int unit) {
;     OPQ_TID;
;     const int b = unit >> 7, n = (unit >> 1) & 63, ch = (unit & 1) * 512 + 8 * (tid & 63), r8 = tid >> 6;
;     const bf16_t* HL = (const bf16_t*)((float*)p.out) + (size_t)b * SEQ * D + ch; const bf16_t* PC = HL + (size_t)T * D;
;     bf16_t* Z = (bf16_t*)(WSP + WS_Z) + (size_t)(b * SEQ + n * 64) * ZW + ch;
;     float carry[8];
; #pragma unroll
;     for (int i = 0; i < 8; ++i) carry[i] = 0.f;
;     int m0 = 0;
;     for (; m0 + 4 <= n; m0 += 4) { u32x4 pp[4], hh4[4];
; #pragma unroll
;         for (int i = 0; i < 4; ++i) { const size_t o = (size_t)((m0 + i) * 64 + 63) * D; pp[i] = *(const u32x4*)(PC + o); hh4[i] = *(const u32x4*)(HL + o); }
; #pragma unroll
;         for (int i = 0; i < 4; ++i)
; #pragma unroll
;             for (int c = 0; c < 4; ++c) { carry[2 * c] = carry[2 * c] * bf2f(pp[i][c] & 0xffffu) + bf2f(hh4[i][c] & 0xffffu); carry[2 * c + 1] = carry[2 * c + 1] * bf2f(pp[i][c] >> 16) + bf2f(hh4[i][c] >> 16); } }
.LBB0_209:
	s_ashr_i32 s20, s37, 7
	v_readfirstlane_b32 s16, v44
	v_readfirstlane_b32 s17, v45
	v_mov_b32_e32 v12, v162
	s_ashr_i32 s21, s20, 31
	s_and_b32 s41, s25, 0x200
	s_bfe_u32 s40, s37, 0x60001
	v_lshlrev_b32_e32 v0, 3, v12
	s_lshl_b64 s[4:5], s[20:21], 23
	v_and_b32_e32 v13, 0x1f8, v0
	s_cmp_lt_u32 s40, 4
	v_mov_b32_e32 v1, 0
	v_mov_b32_e32 v0, 0
	v_mov_b32_e32 v7, 0
	v_mov_b32_e32 v6, 0
	v_mov_b32_e32 v3, 0
	v_mov_b32_e32 v2, 0
	v_mov_b32_e32 v9, 0
	v_mov_b32_e32 v8, 0
	s_mov_b32 s10, 0
	v_add_lshl_u32 v4, s41, v13, 1
	s_cmp_eq_u32 s40, 0
	s_cbranch_scc1 .Lrgb_par_done
	v_lshrrev_b32_e32 v30, 6, v12
	s_add_i32 s21, s40, 7
	s_lshr_b32 s21, s21, 3
	v_readfirstlane_b32 s98, v30
	s_add_u32 s22, s27, s4
	s_addc_u32 s23, s28, s5
	s_add_i32 s101, s40, -1
	s_nop 3
	s_mul_i32 s99, s98, s21
	s_add_i32 s100, s99, s21
	s_min_u32 s100, s100, s40
	s_sub_i32 s100, s100, s99
	s_max_i32 s100, s100, 0
	s_add_i32 s10, s99, 0
	s_min_u32 s10, s10, s101
	s_lshl_b32 s10, s10, 17
	v_add_u32_e32 v124, s10, v4
	s_add_i32 s10, s99, 1
	s_min_u32 s10, s10, s101
	s_lshl_b32 s10, s10, 17
	v_add_u32_e32 v125, s10, v4
	s_add_i32 s10, s99, 2
	s_min_u32 s10, s10, s101
	s_lshl_b32 s10, s10, 17
	v_add_u32_e32 v126, s10, v4
	s_add_i32 s10, s99, 3
	s_min_u32 s10, s10, s101
	s_lshl_b32 s10, s10, 17
	v_add_u32_e32 v127, s10, v4
	s_add_i32 s10, s99, 4
	s_min_u32 s10, s10, s101
	s_lshl_b32 s10, s10, 17
	v_add_u32_e32 v128, s10, v4
	s_add_i32 s10, s99, 5
	s_min_u32 s10, s10, s101
	s_lshl_b32 s10, s10, 17
	v_add_u32_e32 v129, s10, v4
	s_add_i32 s10, s99, 6
	s_min_u32 s10, s10, s101
	s_lshl_b32 s10, s10, 17
	v_add_u32_e32 v130, s10, v4
	s_add_i32 s10, s99, 7
	s_min_u32 s10, s10, s101
	s_lshl_b32 s10, s10, 17
	v_add_u32_e32 v131, s10, v4
	s_sub_u32 s98, s22, 0x2000000
	s_subb_u32 s99, s23, 0
	v_mov_b32_e32 v14, 1.0
	v_mov_b32_e32 v15, 1.0
	v_mov_b32_e32 v22, 0
	v_mov_b32_e32 v23, 0
	v_mov_b32_e32 v16, 1.0
	v_mov_b32_e32 v17, 1.0
	v_mov_b32_e32 v24, 0
	v_mov_b32_e32 v25, 0
	v_mov_b32_e32 v18, 1.0
	v_mov_b32_e32 v19, 1.0
	v_mov_b32_e32 v26, 0
	v_mov_b32_e32 v27, 0
	v_mov_b32_e32 v20, 1.0
	v_mov_b32_e32 v21, 1.0
	v_mov_b32_e32 v28, 0
	v_mov_b32_e32 v29, 0
	global_load_dwordx4 v[60:63], v124, s[22:23]
	global_load_dwordx4 v[64:67], v124, s[98:99]
	global_load_dwordx4 v[68:71], v125, s[22:23]
	global_load_dwordx4 v[72:75], v125, s[98:99]
	global_load_dwordx4 v[76:79], v126, s[22:23]
	global_load_dwordx4 v[80:83], v126, s[98:99]
	global_load_dwordx4 v[84:87], v127, s[22:23]
	global_load_dwordx4 v[88:91], v127, s[98:99]
	global_load_dwordx4 v[92:95], v128, s[22:23]
	global_load_dwordx4 v[96:99], v128, s[98:99]
	global_load_dwordx4 v[100:103], v129, s[22:23]
	global_load_dwordx4 v[104:107], v129, s[98:99]
	global_load_dwordx4 v[108:111], v130, s[22:23]
	global_load_dwordx4 v[112:115], v130, s[98:99]
	global_load_dwordx4 v[116:119], v131, s[22:23]
	global_load_dwordx4 v[120:123], v131, s[98:99]
	s_cmp_gt_u32 s100, 0
	s_cbranch_scc0 .Lrgb_par_cend
	s_waitcnt vmcnt(14)
	v_lshlrev_b32_e32 v132, 16, v60
	v_and_b32_e32 v133, 0xffff0000, v60
	v_lshlrev_b32_e32 v140, 16, v64
	v_and_b32_e32 v141, 0xffff0000, v64
	v_lshlrev_b32_e32 v134, 16, v61
	v_and_b32_e32 v135, 0xffff0000, v61
	v_lshlrev_b32_e32 v142, 16, v65
	v_and_b32_e32 v143, 0xffff0000, v65
	v_lshlrev_b32_e32 v136, 16, v62
	v_and_b32_e32 v137, 0xffff0000, v62
	v_lshlrev_b32_e32 v144, 16, v66
	v_and_b32_e32 v145, 0xffff0000, v66
	v_lshlrev_b32_e32 v138, 16, v63
	v_and_b32_e32 v139, 0xffff0000, v63
	v_lshlrev_b32_e32 v146, 16, v67
	v_and_b32_e32 v147, 0xffff0000, v67
	v_pk_fma_f32 v[22:23], v[22:23], v[132:133], v[140:141]
	v_pk_mul_f32 v[14:15], v[14:15], v[132:133]
	v_pk_fma_f32 v[24:25], v[24:25], v[134:135], v[142:143]
	v_pk_mul_f32 v[16:17], v[16:17], v[134:135]
	v_pk_fma_f32 v[26:27], v[26:27], v[136:137], v[144:145]
	v_pk_mul_f32 v[18:19], v[18:19], v[136:137]
	v_pk_fma_f32 v[28:29], v[28:29], v[138:139], v[146:147]
	v_pk_mul_f32 v[20:21], v[20:21], v[138:139]
	s_cmp_gt_u32 s100, 1
	s_cbranch_scc0 .Lrgb_par_cend
	s_waitcnt vmcnt(12)
	v_lshlrev_b32_e32 v132, 16, v68
	v_and_b32_e32 v133, 0xffff0000, v68
	v_lshlrev_b32_e32 v140, 16, v72
	v_and_b32_e32 v141, 0xffff0000, v72
	v_lshlrev_b32_e32 v134, 16, v69
	v_and_b32_e32 v135, 0xffff0000, v69
	v_lshlrev_b32_e32 v142, 16, v73
	v_and_b32_e32 v143, 0xffff0000, v73
	v_lshlrev_b32_e32 v136, 16, v70
	v_and_b32_e32 v137, 0xffff0000, v70
	v_lshlrev_b32_e32 v144, 16, v74
	v_and_b32_e32 v145, 0xffff0000, v74
	v_lshlrev_b32_e32 v138, 16, v71
	v_and_b32_e32 v139, 0xffff0000, v71
	v_lshlrev_b32_e32 v146, 16, v75
	v_and_b32_e32 v147, 0xffff0000, v75
	v_pk_fma_f32 v[22:23], v[22:23], v[132:133], v[140:141]
	v_pk_mul_f32 v[14:15], v[14:15], v[132:133]
	v_pk_fma_f32 v[24:25], v[24:25], v[134:135], v[142:143]
	v_pk_mul_f32 v[16:17], v[16:17], v[134:135]
	v_pk_fma_f32 v[26:27], v[26:27], v[136:137], v[144:145]
	v_pk_mul_f32 v[18:19], v[18:19], v[136:137]
	v_pk_fma_f32 v[28:29], v[28:29], v[138:139], v[146:147]
	v_pk_mul_f32 v[20:21], v[20:21], v[138:139]
	s_cmp_gt_u32 s100, 2
	s_cbranch_scc0 .Lrgb_par_cend
	s_waitcnt vmcnt(10)
	v_lshlrev_b32_e32 v132, 16, v76
	v_and_b32_e32 v133, 0xffff0000, v76
	v_lshlrev_b32_e32 v140, 16, v80
	v_and_b32_e32 v141, 0xffff0000, v80
	v_lshlrev_b32_e32 v134, 16, v77
	v_and_b32_e32 v135, 0xffff0000, v77
	v_lshlrev_b32_e32 v142, 16, v81
	v_and_b32_e32 v143, 0xffff0000, v81
	v_lshlrev_b32_e32 v136, 16, v78
	v_and_b32_e32 v137, 0xffff0000, v78
	v_lshlrev_b32_e32 v144, 16, v82
	v_and_b32_e32 v145, 0xffff0000, v82
	v_lshlrev_b32_e32 v138, 16, v79
	v_and_b32_e32 v139, 0xffff0000, v79
	v_lshlrev_b32_e32 v146, 16, v83
	v_and_b32_e32 v147, 0xffff0000, v83
	v_pk_fma_f32 v[22:23], v[22:23], v[132:133], v[140:141]
	v_pk_mul_f32 v[14:15], v[14:15], v[132:133]
	v_pk_fma_f32 v[24:25], v[24:25], v[134:135], v[142:143]
	v_pk_mul_f32 v[16:17], v[16:17], v[134:135]
	v_pk_fma_f32 v[26:27], v[26:27], v[136:137], v[144:145]
	v_pk_mul_f32 v[18:19], v[18:19], v[136:137]
	v_pk_fma_f32 v[28:29], v[28:29], v[138:139], v[146:147]
	v_pk_mul_f32 v[20:21], v[20:21], v[138:139]
	s_cmp_gt_u32 s100, 3
	s_cbranch_scc0 .Lrgb_par_cend
; __device__ __forceinline__ float bf2f(unsigned h) { return __uint_as_float(h << 16); }
; __device__ __forceinline__ void rg_b_unit(const Params& p, int unit) {
;     ...
;     for (; m0 + 4 <= n; m0 += 4) { u32x4 pp[4], hh4[4];
; #pragma unroll
;         for (int i = 0; i < 4; ++i) { const size_t o = (size_t)((m0 + i) * 64 + 63) * D; pp[i] = *(const u32x4*)(PC + o); hh4[i] = *(const u32x4*)(HL + o); }
; #pragma unroll
;         for (int i = 0; i < 4; ++i)
; #pragma unroll
;             for (int c = 0; c < 4; ++c) { carry[2 * c] = carry[2 * c] * bf2f(pp[i][c] & 0xffffu) + bf2f(hh4[i][c] & 0xffffu); carry[2 * c + 1] = carry[2 * c + 1] * bf2f(pp[i][c] >> 16) + bf2f(hh4[i][c] >> 16); } }
	s_waitcnt vmcnt(8)
	v_lshlrev_b32_e32 v132, 16, v84
	v_and_b32_e32 v133, 0xffff0000, v84
	v_lshlrev_b32_e32 v140, 16, v88
	v_and_b32_e32 v141, 0xffff0000, v88
	v_lshlrev_b32_e32 v134, 16, v85
	v_and_b32_e32 v135, 0xffff0000, v85
	v_lshlrev_b32_e32 v142, 16, v89
	v_and_b32_e32 v143, 0xffff0000, v89
	v_lshlrev_b32_e32 v136, 16, v86
	v_and_b32_e32 v137, 0xffff0000, v86
	v_lshlrev_b32_e32 v144, 16, v90
	v_and_b32_e32 v145, 0xffff0000, v90
	v_lshlrev_b32_e32 v138, 16, v87
	v_and_b32_e32 v139, 0xffff0000, v87
	v_lshlrev_b32_e32 v146, 16, v91
	v_and_b32_e32 v147, 0xffff0000, v91
	v_pk_fma_f32 v[22:23], v[22:23], v[132:133], v[140:141]
	v_pk_mul_f32 v[14:15], v[14:15], v[132:133]
	v_pk_fma_f32 v[24:25], v[24:25], v[134:135], v[142:143]
	v_pk_mul_f32 v[16:17], v[16:17], v[134:135]
	v_pk_fma_f32 v[26:27], v[26:27], v[136:137], v[144:145]
	v_pk_mul_f32 v[18:19], v[18:19], v[136:137]
	v_pk_fma_f32 v[28:29], v[28:29], v[138:139], v[146:147]
	v_pk_mul_f32 v[20:21], v[20:21], v[138:139]
	s_cmp_gt_u32 s100, 4
	s_cbranch_scc0 .Lrgb_par_cend
	s_waitcnt vmcnt(6)
	v_lshlrev_b32_e32 v132, 16, v92
	v_and_b32_e32 v133, 0xffff0000, v92
	v_lshlrev_b32_e32 v140, 16, v96
	v_and_b32_e32 v141, 0xffff0000, v96
	v_lshlrev_b32_e32 v134, 16, v93
	v_and_b32_e32 v135, 0xffff0000, v93
	v_lshlrev_b32_e32 v142, 16, v97
	v_and_b32_e32 v143, 0xffff0000, v97
	v_lshlrev_b32_e32 v136, 16, v94
	v_and_b32_e32 v137, 0xffff0000, v94
	v_lshlrev_b32_e32 v144, 16, v98
	v_and_b32_e32 v145, 0xffff0000, v98
	v_lshlrev_b32_e32 v138, 16, v95
	v_and_b32_e32 v139, 0xffff0000, v95
	v_lshlrev_b32_e32 v146, 16, v99
	v_and_b32_e32 v147, 0xffff0000, v99
	v_pk_fma_f32 v[22:23], v[22:23], v[132:133], v[140:141]
	v_pk_mul_f32 v[14:15], v[14:15], v[132:133]
	v_pk_fma_f32 v[24:25], v[24:25], v[134:135], v[142:143]
	v_pk_mul_f32 v[16:17], v[16:17], v[134:135]
	v_pk_fma_f32 v[26:27], v[26:27], v[136:137], v[144:145]
	v_pk_mul_f32 v[18:19], v[18:19], v[136:137]
	v_pk_fma_f32 v[28:29], v[28:29], v[138:139], v[146:147]
	v_pk_mul_f32 v[20:21], v[20:21], v[138:139]
	s_cmp_gt_u32 s100, 5
	s_cbranch_scc0 .Lrgb_par_cend
	s_waitcnt vmcnt(4)
	v_lshlrev_b32_e32 v132, 16, v100
	v_and_b32_e32 v133, 0xffff0000, v100
	v_lshlrev_b32_e32 v140, 16, v104
	v_and_b32_e32 v141, 0xffff0000, v104
	v_lshlrev_b32_e32 v134, 16, v101
	v_and_b32_e32 v135, 0xffff0000, v101
	v_lshlrev_b32_e32 v142, 16, v105
	v_and_b32_e32 v143, 0xffff0000, v105
	v_lshlrev_b32_e32 v136, 16, v102
	v_and_b32_e32 v137, 0xffff0000, v102
	v_lshlrev_b32_e32 v144, 16, v106
	v_and_b32_e32 v145, 0xffff0000, v106
	v_lshlrev_b32_e32 v138, 16, v103
	v_and_b32_e32 v139, 0xffff0000, v103
	v_lshlrev_b32_e32 v146, 16, v107
	v_and_b32_e32 v147, 0xffff0000, v107
	v_pk_fma_f32 v[22:23], v[22:23], v[132:133], v[140:141]
	v_pk_mul_f32 v[14:15], v[14:15], v[132:133]
	v_pk_fma_f32 v[24:25], v[24:25], v[134:135], v[142:143]
	v_pk_mul_f32 v[16:17], v[16:17], v[134:135]
	v_pk_fma_f32 v[26:27], v[26:27], v[136:137], v[144:145]
	v_pk_mul_f32 v[18:19], v[18:19], v[136:137]
	v_pk_fma_f32 v[28:29], v[28:29], v[138:139], v[146:147]
	v_pk_mul_f32 v[20:21], v[20:21], v[138:139]
	s_cmp_gt_u32 s100, 6
	s_cbranch_scc0 .Lrgb_par_cend
	s_waitcnt vmcnt(2)
	v_lshlrev_b32_e32 v132, 16, v108
	v_and_b32_e32 v133, 0xffff0000, v108
	v_lshlrev_b32_e32 v140, 16, v112
	v_and_b32_e32 v141, 0xffff0000, v112
	v_lshlrev_b32_e32 v134, 16, v109
	v_and_b32_e32 v135, 0xffff0000, v109
	v_lshlrev_b32_e32 v142, 16, v113
	v_and_b32_e32 v143, 0xffff0000, v113
	v_lshlrev_b32_e32 v136, 16, v110
	v_and_b32_e32 v137, 0xffff0000, v110
	v_lshlrev_b32_e32 v144, 16, v114
	v_and_b32_e32 v145, 0xffff0000, v114
	v_lshlrev_b32_e32 v138, 16, v111
	v_and_b32_e32 v139, 0xffff0000, v111
	v_lshlrev_b32_e32 v146, 16, v115
	v_and_b32_e32 v147, 0xffff0000, v115
	v_pk_fma_f32 v[22:23], v[22:23], v[132:133], v[140:141]
	v_pk_mul_f32 v[14:15], v[14:15], v[132:133]
	v_pk_fma_f32 v[24:25], v[24:25], v[134:135], v[142:143]
	v_pk_mul_f32 v[16:17], v[16:17], v[134:135]
	v_pk_fma_f32 v[26:27], v[26:27], v[136:137], v[144:145]
	v_pk_mul_f32 v[18:19], v[18:19], v[136:137]
	v_pk_fma_f32 v[28:29], v[28:29], v[138:139], v[146:147]
	v_pk_mul_f32 v[20:21], v[20:21], v[138:139]
	s_cmp_gt_u32 s100, 7
	s_cbranch_scc0 .Lrgb_par_cend
	s_waitcnt vmcnt(0)
	v_lshlrev_b32_e32 v132, 16, v116
	v_and_b32_e32 v133, 0xffff0000, v116
	v_lshlrev_b32_e32 v140, 16, v120
	v_and_b32_e32 v141, 0xffff0000, v120
	v_lshlrev_b32_e32 v134, 16, v117
	v_and_b32_e32 v135, 0xffff0000, v117
	v_lshlrev_b32_e32 v142, 16, v121
	v_and_b32_e32 v143, 0xffff0000, v121
	v_lshlrev_b32_e32 v136, 16, v118
	v_and_b32_e32 v137, 0xffff0000, v118
	v_lshlrev_b32_e32 v144, 16, v122
	v_and_b32_e32 v145, 0xffff0000, v122
	v_lshlrev_b32_e32 v138, 16, v119
	v_and_b32_e32 v139, 0xffff0000, v119
	v_lshlrev_b32_e32 v146, 16, v123
	v_and_b32_e32 v147, 0xffff0000, v123
	v_pk_fma_f32 v[22:23], v[22:23], v[132:133], v[140:141]
	v_pk_mul_f32 v[14:15], v[14:15], v[132:133]
	v_pk_fma_f32 v[24:25], v[24:25], v[134:135], v[142:143]
	v_pk_mul_f32 v[16:17], v[16:17], v[134:135]
	v_pk_fma_f32 v[26:27], v[26:27], v[136:137], v[144:145]
	v_pk_mul_f32 v[18:19], v[18:19], v[136:137]
	v_pk_fma_f32 v[28:29], v[28:29], v[138:139], v[146:147]
	v_pk_mul_f32 v[20:21], v[20:21], v[138:139]
; __device__ __forceinline__ float bf2f(unsigned h) { return __uint_as_float(h << 16); }
; __device__ __forceinline__ void rg_b_unit(const Params& p, int unit) {
;     ...
;     float carry[8];
; #pragma unroll
;     for (int i = 0; i < 8; ++i) carry[i] = 0.f;
;     int m0 = 0;
;     for (; m0 + 4 <= n; m0 += 4) { u32x4 pp[4], hh4[4];
; #pragma unroll
;         for (int i = 0; i < 4; ++i) { const size_t o = (size_t)((m0 + i) * 64 + 63) * D; pp[i] = *(const u32x4*)(PC + o); hh4[i] = *(const u32x4*)(HL + o); }
; #pragma unroll
;         for (int i = 0; i < 4; ++i)
; #pragma unroll
;             for (int c = 0; c < 4; ++c) { carry[2 * c] = carry[2 * c] * bf2f(pp[i][c] & 0xffffu) + bf2f(hh4[i][c] & 0xffffu); carry[2 * c + 1] = carry[2 * c + 1] * bf2f(pp[i][c] >> 16) + bf2f(hh4[i][c] >> 16); } }
;     for (; m0 < n; ++m0) { const size_t o = (size_t)(m0 * 64 + 63) * D; const u32x4 pp = *(const u32x4*)(PC + o), hh4 = *(const u32x4*)(HL + o);
; #pragma unroll
;         for (int c = 0; c < 4; ++c) { carry[2 * c] = carry[2 * c] * bf2f(pp[c] & 0xffffu) + bf2f(hh4[c] & 0xffffu); carry[2 * c + 1] = carry[2 * c + 1] * bf2f(pp[c] >> 16) + bf2f(hh4[c] >> 16); } }
; #pragma unroll 4
;     for (int tq = 0; tq < 8; ++tq) { const int t = 8 * tq + r8; const size_t o = (size_t)(n * 64 + t) * D;
;         const u32x4 hv = __builtin_nontemporal_load((const u32x4*)(HL + o)), pv = __builtin_nontemporal_load((const u32x4*)(PC + o)), gv = __builtin_nontemporal_load((const u32x4*)(Z + (size_t)t * ZW + 1024)); u32x4 ov;
.Lrgb_par_cend:
	s_waitcnt vmcnt(0)
	v_lshlrev_b32_e32 v30, 6, v12
	v_and_b32_e32 v31, 63, v12
	v_lshlrev_b32_e32 v31, 6, v31
	ds_write_b128 v30, v[14:17]
	ds_write_b128 v30, v[18:21] offset:16
	ds_write_b128 v30, v[22:25] offset:32
	ds_write_b128 v30, v[26:29] offset:48
	s_waitcnt lgkmcnt(0)
	s_barrier
	ds_read_b128 v[60:63], v31 offset:0
	ds_read_b128 v[64:67], v31 offset:16
	ds_read_b128 v[68:71], v31 offset:32
	ds_read_b128 v[72:75], v31 offset:48
	ds_read_b128 v[76:79], v31 offset:4096
	ds_read_b128 v[80:83], v31 offset:4112
	ds_read_b128 v[84:87], v31 offset:4128
	ds_read_b128 v[88:91], v31 offset:4144
	ds_read_b128 v[92:95], v31 offset:8192
	ds_read_b128 v[96:99], v31 offset:8208
	ds_read_b128 v[100:103], v31 offset:8224
	ds_read_b128 v[104:107], v31 offset:8240
	ds_read_b128 v[108:111], v31 offset:12288
	ds_read_b128 v[112:115], v31 offset:12304
	ds_read_b128 v[116:119], v31 offset:12320
	ds_read_b128 v[120:123], v31 offset:12336
	s_waitcnt lgkmcnt(0)
	v_pk_fma_f32 v[8:9], v[8:9], v[60:61], v[68:69]
	v_pk_fma_f32 v[2:3], v[2:3], v[62:63], v[70:71]
	v_pk_fma_f32 v[6:7], v[6:7], v[64:65], v[72:73]
	v_pk_fma_f32 v[0:1], v[0:1], v[66:67], v[74:75]
	v_pk_fma_f32 v[8:9], v[8:9], v[76:77], v[84:85]
	v_pk_fma_f32 v[2:3], v[2:3], v[78:79], v[86:87]
	v_pk_fma_f32 v[6:7], v[6:7], v[80:81], v[88:89]
	v_pk_fma_f32 v[0:1], v[0:1], v[82:83], v[90:91]
	v_pk_fma_f32 v[8:9], v[8:9], v[92:93], v[100:101]
	v_pk_fma_f32 v[2:3], v[2:3], v[94:95], v[102:103]
	v_pk_fma_f32 v[6:7], v[6:7], v[96:97], v[104:105]
	v_pk_fma_f32 v[0:1], v[0:1], v[98:99], v[106:107]
	v_pk_fma_f32 v[8:9], v[8:9], v[108:109], v[116:117]
	v_pk_fma_f32 v[2:3], v[2:3], v[110:111], v[118:119]
	v_pk_fma_f32 v[6:7], v[6:7], v[112:113], v[120:121]
	v_pk_fma_f32 v[0:1], v[0:1], v[114:115], v[122:123]
	ds_read_b128 v[60:63], v31 offset:16384
	ds_read_b128 v[64:67], v31 offset:16400
	ds_read_b128 v[68:71], v31 offset:16416
	ds_read_b128 v[72:75], v31 offset:16432
	ds_read_b128 v[76:79], v31 offset:20480
	ds_read_b128 v[80:83], v31 offset:20496
	ds_read_b128 v[84:87], v31 offset:20512
	ds_read_b128 v[88:91], v31 offset:20528
	ds_read_b128 v[92:95], v31 offset:24576
	ds_read_b128 v[96:99], v31 offset:24592
	ds_read_b128 v[100:103], v31 offset:24608
	ds_read_b128 v[104:107], v31 offset:24624
	ds_read_b128 v[108:111], v31 offset:28672
	ds_read_b128 v[112:115], v31 offset:28688
	ds_read_b128 v[116:119], v31 offset:28704
	ds_read_b128 v[120:123], v31 offset:28720
	s_waitcnt lgkmcnt(0)
	v_pk_fma_f32 v[8:9], v[8:9], v[60:61], v[68:69]
	v_pk_fma_f32 v[2:3], v[2:3], v[62:63], v[70:71]
	v_pk_fma_f32 v[6:7], v[6:7], v[64:65], v[72:73]
	v_pk_fma_f32 v[0:1], v[0:1], v[66:67], v[74:75]
	v_pk_fma_f32 v[8:9], v[8:9], v[76:77], v[84:85]
	v_pk_fma_f32 v[2:3], v[2:3], v[78:79], v[86:87]
	v_pk_fma_f32 v[6:7], v[6:7], v[80:81], v[88:89]
	v_pk_fma_f32 v[0:1], v[0:1], v[82:83], v[90:91]
	v_pk_fma_f32 v[8:9], v[8:9], v[92:93], v[100:101]
	v_pk_fma_f32 v[2:3], v[2:3], v[94:95], v[102:103]
	v_pk_fma_f32 v[6:7], v[6:7], v[96:97], v[104:105]
	v_pk_fma_f32 v[0:1], v[0:1], v[98:99], v[106:107]
	v_pk_fma_f32 v[8:9], v[8:9], v[108:109], v[116:117]
	v_pk_fma_f32 v[2:3], v[2:3], v[110:111], v[118:119]
	v_pk_fma_f32 v[6:7], v[6:7], v[112:113], v[120:121]
	v_pk_fma_f32 v[0:1], v[0:1], v[114:115], v[122:123]
	s_barrier
.Lrgb_par_done:
	s_lshr_b32 s21, s37, 1
.LBB0_217:
	s_and_b32 s10, s21, 63
	s_lshl_b32 s10, s10, 6
	s_lshl_b32 s20, s20, 12
	s_or_b32 s20, s20, s10
	s_mul_hi_i32 s21, s20, 0x3000
	s_mulk_i32 s20, 0x3000
	s_add_u32 s16, s16, s20
	s_addc_u32 s17, s17, s21
	v_ashrrev_i32_e32 v16, 6, v12
	v_mov_b32_e32 v12, v7
	v_mov_b32_e32 v13, v1
	v_mov_b32_e32 v7, v0
	v_mov_b64_e32 v[0:1], s[16:17]
	v_mad_i64_i32 v[14:15], s[16:17], v16, s30, v[0:1]
	v_add_u32_e32 v0, s10, v16
	v_mov_b32_e32 v10, v9
	v_mov_b32_e32 v9, v2
	v_add_u32_e32 v2, 24, v0
	v_mov_b32_e32 v11, v3
	v_ashrrev_i32_e32 v3, 31, v2
	s_add_u32 s4, s8, s4
	v_lshlrev_b64 v[2:3], 11, v[2:3]
	s_addc_u32 s5, s9, s5
	v_ashrrev_i32_e32 v1, 31, v0
	v_lshl_add_u64 v[16:17], s[4:5], 0, v[2:3]
	v_lshlrev_b64 v[2:3], 11, v[0:1]
	v_lshl_add_u64 v[18:19], s[4:5], 0, v[2:3]
	v_add_u32_e32 v2, 16, v0
	v_add_u32_e32 v0, 8, v0
	v_ashrrev_i32_e32 v3, 31, v2
	v_ashrrev_i32_e32 v1, 31, v0
	v_lshlrev_b64 v[2:3], 11, v[2:3]
	v_lshlrev_b64 v[0:1], 11, v[0:1]
	v_lshl_add_u64 v[20:21], s[4:5], 0, v[2:3]
	s_mov_b32 s10, 8
	v_lshl_add_u64 v[22:23], s[4:5], 0, v[0:1]

; __global__ void __launch_bounds__(NT, 2) mk_fwd(Params p) {
	.amdhsa_kernel _Z6mk_fwd6Params
		.amdhsa_group_segment_fixed_size 0
		.amdhsa_private_segment_fixed_size 0
		.amdhsa_kernarg_size 536
		.amdhsa_user_sgpr_count 2
		.amdhsa_user_sgpr_dispatch_ptr 0
		.amdhsa_user_sgpr_queue_ptr 0
		.amdhsa_user_sgpr_kernarg_segment_ptr 1
		.amdhsa_user_sgpr_dispatch_id 0
		.amdhsa_user_sgpr_kernarg_preload_length 0
		.amdhsa_user_sgpr_kernarg_preload_offset 0
		.amdhsa_user_sgpr_private_segment_size 0
		.amdhsa_uses_dynamic_stack 0
		.amdhsa_enable_private_segment 0
		.amdhsa_system_sgpr_workgroup_id_x 1
		.amdhsa_system_sgpr_workgroup_id_y 0
		.amdhsa_system_sgpr_workgroup_id_z 0
		.amdhsa_system_sgpr_workgroup_info 0
		.amdhsa_system_vgpr_workitem_id 2
		.amdhsa_next_free_vgpr 237
		.amdhsa_next_free_sgpr 102
		.amdhsa_accum_offset 240
		.amdhsa_reserve_vcc 1
		.amdhsa_float_round_mode_32 0
		.amdhsa_float_round_mode_16_64 0
		.amdhsa_float_denorm_mode_32 3
		.amdhsa_float_denorm_mode_16_64 3
		.amdhsa_dx10_clamp 1
		.amdhsa_ieee_mode 1
		.amdhsa_fp16_overflow 0
		.amdhsa_tg_split 0
		.amdhsa_exception_fp_ieee_invalid_op 0
		.amdhsa_exception_fp_denorm_src 0
		.amdhsa_exception_fp_ieee_div_zero 0
		.amdhsa_exception_fp_ieee_overflow 0
		.amdhsa_exception_fp_ieee_underflow 0
		.amdhsa_exception_fp_ieee_inexact 0
		.amdhsa_exception_int_div_zero 0
	.end_amdhsa_kernel

; __global__ void __launch_bounds__(NT, 2) mk_fwd(Params p) {
amdhsa.kernels:
  - .agpr_count:     0
    .args:
      - .offset:         0
        .size:           280
        .value_kind:     by_value
      - .offset:         280
        .size:           4
        .value_kind:     hidden_block_count_x
      - .offset:         284
        .size:           4
        .value_kind:     hidden_block_count_y
      - .offset:         288
        .size:           4
        .value_kind:     hidden_block_count_z
      - .offset:         292
        .size:           2
        .value_kind:     hidden_group_size_x
      - .offset:         294
        .size:           2
        .value_kind:     hidden_group_size_y
      - .offset:         296
        .size:           2
        .value_kind:     hidden_group_size_z
      - .offset:         298
        .size:           2
        .value_kind:     hidden_remainder_x
      - .offset:         300
        .size:           2
        .value_kind:     hidden_remainder_y
      - .offset:         302
        .size:           2
        .value_kind:     hidden_remainder_z
      - .offset:         320
        .size:           8
        .value_kind:     hidden_global_offset_x
      - .offset:         328
        .size:           8
        .value_kind:     hidden_global_offset_y
      - .offset:         336
        .size:           8
        .value_kind:     hidden_global_offset_z
      - .offset:         344
        .size:           2
        .value_kind:     hidden_grid_dims
      - .offset:         368
        .size:           8
        .value_kind:     hidden_multigrid_sync_arg
      - .offset:         400
        .size:           4
        .value_kind:     hidden_dynamic_lds_size
    .group_segment_fixed_size: 0
    .kernarg_segment_align: 8
    .kernarg_segment_size: 536
    .language:       OpenCL C
    .language_version:
      - 2
      - 0
    .max_flat_workgroup_size: 512
    .name:           _Z6mk_fwd6Params
    .private_segment_fixed_size: 0
    .sgpr_count:     108
    .sgpr_spill_count: 15
    .symbol:         _Z6mk_fwd6Params.kd
    .uniform_work_group_size: 1
    .uses_dynamic_stack: false
    .vgpr_count:     237
    .vgpr_spill_count: 0
    .wavefront_size: 64
